# norm-phase wave sums: ds_bpermute xor-butterfly replaced by DPP adds plus permlane16/32 swaps (on top of the batched weight-conversion loads)
# speedup vs baseline: 1.0077x; 1.0039x over previous
; DI float wave_sum(float v) {
; #pragma unroll
;   for (int o = 32; o; o >>= 1) v += __shfl_xor(v, o);
;   return v;
; }
; template <bool F32OUT>
; DI void rmsnorm_rows(const float* X, const float* __restrict__ g, void* outp, int nrows, unsigned char* __restrict__ out8 = nullptr) {
;     ...
;   for (int row = gw; row < nrows; row += nw) {
;     const f32x4* xr = (const f32x4*)(X + (size_t)row * 2048);
;     f32x4 v[8];
;     float ss = 0.f;
; #pragma unroll
;     for (int i = 0; i < 8; ++i) { v[i] = xr[lane + 64 * i]; ss += v[i][0] * v[i][0] + v[i][1] * v[i][1] + v[i][2] * v[i][2] + v[i][3] * v[i][3]; }
;     ss = wave_sum(ss);
;     const float r = rsqrtf(ss * (1.f / 2048.f) + 1e-6f);
.LBB0_25:
	global_load_dwordx4 v[36:39], v[52:53], off
	global_load_dwordx4 v[32:35], v[52:53], off offset:1024
	global_load_dwordx4 v[44:47], v[52:53], off offset:2048
	global_load_dwordx4 v[40:43], v[52:53], off offset:3072
	global_load_dwordx4 v[62:65], v[52:53], off offset:-4096
	global_load_dwordx4 v[66:69], v[52:53], off offset:-3072
	global_load_dwordx4 v[70:73], v[52:53], off offset:-2048
	global_load_dwordx4 v[74:77], v[52:53], off offset:-1024
	v_add_u32_e32 v48, s28, v48
	v_cmp_lt_i32_e32 vcc, s15, v48
	s_or_b64 s[12:13], vcc, s[12:13]
	v_lshl_add_u64 v[52:53], v[52:53], 0, s[10:11]
	s_waitcnt vmcnt(7)
	v_mov_b32_e32 v80, v37
	s_waitcnt vmcnt(6)
	v_mov_b32_e32 v81, v33
	v_mov_b32_e32 v78, v36
	v_mov_b32_e32 v79, v32
	s_waitcnt vmcnt(3)
	v_mul_f32_e32 v61, v63, v63
	s_waitcnt vmcnt(2)
	v_mul_f32_e32 v94, v67, v67
	s_waitcnt vmcnt(1)
	v_mul_f32_e32 v95, v71, v71
	v_fmac_f32_e32 v61, v62, v62
	v_fmac_f32_e32 v94, v66, v66
	s_waitcnt vmcnt(0)
	v_mul_f32_e32 v96, v75, v75
	v_fmac_f32_e32 v95, v70, v70
	v_fmac_f32_e32 v61, v64, v64
	v_fmac_f32_e32 v94, v68, v68
	v_pk_mul_f32 v[80:81], v[80:81], v[80:81]
	v_fmac_f32_e32 v96, v74, v74
	v_fmac_f32_e32 v95, v72, v72
	v_fmac_f32_e32 v61, v65, v65
	v_fmac_f32_e32 v94, v69, v69
	v_mov_b32_e32 v84, v45
	v_mov_b32_e32 v85, v41
	v_mov_b32_e32 v86, v38
	v_mov_b32_e32 v87, v34
	v_pk_fma_f32 v[78:79], v[78:79], v[78:79], v[80:81]
	v_fmac_f32_e32 v96, v76, v76
	v_fmac_f32_e32 v95, v73, v73
	v_add_f32_e32 v61, v61, v94
	v_mov_b32_e32 v82, v44
	v_mov_b32_e32 v83, v40
	v_mov_b32_e32 v90, v39
	v_mov_b32_e32 v91, v35
	v_pk_mul_f32 v[84:85], v[84:85], v[84:85]
	v_pk_fma_f32 v[78:79], v[86:87], v[86:87], v[78:79]
	v_fmac_f32_e32 v96, v77, v77
	v_add_f32_e32 v61, v61, v95
	v_mov_b32_e32 v88, v46
	v_mov_b32_e32 v89, v42
	v_pk_fma_f32 v[80:81], v[82:83], v[82:83], v[84:85]
	v_pk_fma_f32 v[78:79], v[90:91], v[90:91], v[78:79]
	v_add_f32_e32 v61, v61, v96
	v_mov_b32_e32 v92, v47
	v_mov_b32_e32 v93, v43
	v_pk_fma_f32 v[80:81], v[88:89], v[88:89], v[80:81]
	v_add_f32_e32 v61, v61, v78
	v_pk_fma_f32 v[80:81], v[92:93], v[92:93], v[80:81]
	v_add_f32_e32 v61, v61, v79
	v_add_f32_e32 v61, v61, v80
	v_add_f32_e32 v61, v61, v81
	s_nop 1
	v_add_f32_dpp v61, v61, v61 quad_perm:[1,0,3,2] row_mask:0xf bank_mask:0xf
	s_nop 1
	v_add_f32_dpp v61, v61, v61 quad_perm:[2,3,0,1] row_mask:0xf bank_mask:0xf
	s_nop 1
	v_add_f32_dpp v61, v61, v61 row_half_mirror row_mask:0xf bank_mask:0xf
	s_nop 1
	v_add_f32_dpp v61, v61, v61 row_mirror row_mask:0xf bank_mask:0xf
	v_mov_b32_e32 v78, v61
	s_nop 1
	v_permlane16_swap_b32_e32 v78, v61
	v_add_f32_e32 v61, v61, v78
	v_mov_b32_e32 v78, v61
	s_nop 1
	v_permlane32_swap_b32_e32 v78, v61
	v_add_f32_e32 v61, v61, v78
	v_fmamk_f32 v61, v61, 0x3a000000, v49
	v_mul_f32_e32 v78, 0x4b800000, v61
	v_cmp_gt_f32_e32 vcc, s14, v61
	s_nop 1
	v_cndmask_b32_e32 v61, v61, v78, vcc
	v_rsq_f32_e32 v61, v61
	s_nop 0
	v_mul_f32_e32 v78, 0x45800000, v61
	v_cndmask_b32_e32 v78, v61, v78, vcc
	v_pk_mul_f32 v[62:63], v[62:63], v[78:79] op_sel_hi:[1,0]
	v_pk_mul_f32 v[64:65], v[64:65], v[78:79] op_sel_hi:[1,0]
	v_pk_mul_f32 v[66:67], v[66:67], v[78:79] op_sel_hi:[1,0]
	v_pk_mul_f32 v[68:69], v[68:69], v[78:79] op_sel_hi:[1,0]
	v_pk_mul_f32 v[70:71], v[70:71], v[78:79] op_sel_hi:[1,0]
	v_pk_mul_f32 v[72:73], v[72:73], v[78:79] op_sel_hi:[1,0]
	v_pk_mul_f32 v[74:75], v[74:75], v[78:79] op_sel_hi:[1,0]
	v_pk_mul_f32 v[76:77], v[76:77], v[78:79] op_sel_hi:[1,0]
	v_pk_mul_f32 v[36:37], v[36:37], v[78:79] op_sel_hi:[1,0]
	v_pk_mul_f32 v[38:39], v[38:39], v[78:79] op_sel_hi:[1,0]
	v_pk_mul_f32 v[32:33], v[32:33], v[78:79] op_sel_hi:[1,0]
	v_pk_mul_f32 v[34:35], v[34:35], v[78:79] op_sel_hi:[1,0]
	v_pk_mul_f32 v[44:45], v[44:45], v[78:79] op_sel_hi:[1,0]
	v_pk_mul_f32 v[46:47], v[46:47], v[78:79] op_sel_hi:[1,0]
	v_pk_mul_f32 v[40:41], v[40:41], v[78:79] op_sel_hi:[1,0]
	v_pk_mul_f32 v[42:43], v[42:43], v[78:79] op_sel_hi:[1,0]
	v_pk_mul_f32 v[62:63], v[0:1], v[62:63]
	v_pk_mul_f32 v[64:65], v[2:3], v[64:65]
	v_pk_mul_f32 v[66:67], v[4:5], v[66:67]
	v_pk_mul_f32 v[68:69], v[6:7], v[68:69]
	v_pk_mul_f32 v[70:71], v[8:9], v[70:71]
	v_pk_mul_f32 v[72:73], v[10:11], v[72:73]
	v_pk_mul_f32 v[74:75], v[12:13], v[74:75]
	v_pk_mul_f32 v[76:77], v[14:15], v[76:77]
	v_pk_mul_f32 v[36:37], v[16:17], v[36:37]
	v_pk_mul_f32 v[38:39], v[18:19], v[38:39]
	v_pk_mul_f32 v[32:33], v[20:21], v[32:33]
	v_pk_mul_f32 v[34:35], v[22:23], v[34:35]
	v_pk_mul_f32 v[44:45], v[24:25], v[44:45]
	v_pk_mul_f32 v[46:47], v[26:27], v[46:47]
	v_pk_mul_f32 v[40:41], v[28:29], v[40:41]
	v_pk_mul_f32 v[42:43], v[30:31], v[42:43]
	v_cvt_pk_bf16_f32 v62, v62, v63
	v_cvt_pk_bf16_f32 v63, v64, v65
	v_cvt_pk_bf16_f32 v64, v66, v67
	v_cvt_pk_bf16_f32 v65, v68, v69
	v_cvt_pk_bf16_f32 v66, v70, v71
	v_cvt_pk_bf16_f32 v67, v72, v73
	v_cvt_pk_bf16_f32 v68, v74, v75
	v_cvt_pk_bf16_f32 v69, v76, v77
	v_cvt_pk_bf16_f32 v36, v36, v37
	v_cvt_pk_bf16_f32 v37, v38, v39
	v_cvt_pk_bf16_f32 v32, v32, v33
	v_cvt_pk_bf16_f32 v33, v34, v35
	v_cvt_pk_bf16_f32 v34, v44, v45
	v_cvt_pk_bf16_f32 v35, v46, v47
	v_cvt_pk_bf16_f32 v38, v40, v41
	v_cvt_pk_bf16_f32 v39, v42, v43
	global_store_dwordx2 v[50:51], v[62:63], off
	global_store_dwordx2 v[50:51], v[64:65], off offset:512
	global_store_dwordx2 v[50:51], v[66:67], off offset:1024
	global_store_dwordx2 v[50:51], v[68:69], off offset:1536
	global_store_dwordx2 v[50:51], v[36:37], off offset:2048
	global_store_dwordx2 v[50:51], v[32:33], off offset:2560
	global_store_dwordx2 v[50:51], v[34:35], off offset:3072
	global_store_dwordx2 v[50:51], v[38:39], off offset:3584
	v_lshl_add_u64 v[50:51], v[50:51], 0, s[8:9]
	s_andn2_b64 exec, exec, s[12:13]
	s_cbranch_execnz .LBB0_25

; DI float wave_sum(float v) {
; #pragma unroll
;   for (int o = 32; o; o >>= 1) v += __shfl_xor(v, o);
;   return v;
; }
; template <bool F32OUT>
; DI void rmsnorm_rows(const float* X, const float* __restrict__ g, void* outp, int nrows, unsigned char* __restrict__ out8 = nullptr) {
;     ...
;   for (int row = gw; row < nrows; row += nw) {
;     const f32x4* xr = (const f32x4*)(X + (size_t)row * 2048);
;     f32x4 v[8];
;     float ss = 0.f;
; #pragma unroll
;     for (int i = 0; i < 8; ++i) { v[i] = xr[lane + 64 * i]; ss += v[i][0] * v[i][0] + v[i][1] * v[i][1] + v[i][2] * v[i][2] + v[i][3] * v[i][3]; }
;     ss = wave_sum(ss);
;     const float r = rsqrtf(ss * (1.f / 2048.f) + 1e-6f);
; #pragma unroll
;     for (int i = 0; i < 8; ++i) {
;       const f32x4 gg = ((const f32x4*)g)[lane + 64 * i];
;       f32x4 o = {v[i][0] * r * gg[0], v[i][1] * r * gg[1], v[i][2] * r * gg[2], v[i][3] * r * gg[3]};
;       if (F32OUT) ((f32x4*)((float*)outp + (size_t)row * 2048))[lane + 64 * i] = o;
;       else { u32x2 pk = {pk2(o[0], o[1]), pk2(o[2], o[3])}; ((u32x2*)((u16*)outp + (size_t)row * 2048))[lane + 64 * i] = pk; }
;       if (!F32OUT && out8) ((unsigned*)(out8 + (size_t)row * 2048))[lane + 64 * i] = pk4_fp8(o[0] * H_SCALE, o[1] * H_SCALE, o[2] * H_SCALE, o[3] * H_SCALE);
;     }
.LBB0_39:
	global_load_dwordx4 v[76:79], v[68:69], off offset:-4096
	global_load_dwordx4 v[58:61], v[68:69], off offset:-3072
	global_load_dwordx4 v[54:57], v[68:69], off offset:-2048
	global_load_dwordx4 v[50:53], v[68:69], off offset:-1024
	global_load_dwordx4 v[46:49], v[68:69], off
	global_load_dwordx4 v[42:45], v[68:69], off offset:1024
	global_load_dwordx4 v[38:41], v[68:69], off offset:2048
	global_load_dwordx4 v[34:37], v[68:69], off offset:3072
	s_waitcnt vmcnt(7)
	v_mul_f32_e32 v0, v77, v77
	s_waitcnt vmcnt(6)
	v_mul_f32_e32 v63, v59, v59
	s_waitcnt vmcnt(5)
	v_mul_f32_e32 v96, v55, v55
	v_fmac_f32_e32 v0, v76, v76
	v_fmac_f32_e32 v63, v58, v58
	s_waitcnt vmcnt(4)
	v_mul_f32_e32 v97, v51, v51
	s_waitcnt vmcnt(3)
	v_mov_b32_e32 v72, v47
	s_waitcnt vmcnt(2)
	v_mov_b32_e32 v73, v43
	v_fmac_f32_e32 v96, v54, v54
	v_fmac_f32_e32 v0, v78, v78
	v_fmac_f32_e32 v63, v60, v60
	v_mov_b32_e32 v70, v46
	v_mov_b32_e32 v71, v42
	v_fmac_f32_e32 v97, v50, v50
	v_pk_mul_f32 v[72:73], v[72:73], v[72:73]
	v_fmac_f32_e32 v96, v56, v56
	v_fmac_f32_e32 v0, v79, v79
	v_fmac_f32_e32 v63, v61, v61
	v_mov_b32_e32 v74, v48
	v_mov_b32_e32 v75, v44
	s_waitcnt vmcnt(1)
	v_mov_b32_e32 v90, v39
	s_waitcnt vmcnt(0)
	v_mov_b32_e32 v91, v35
	v_fmac_f32_e32 v97, v52, v52
	v_pk_fma_f32 v[70:71], v[70:71], v[70:71], v[72:73]
	v_fmac_f32_e32 v96, v57, v57
	v_add_f32_e32 v0, v0, v63
	v_mov_b32_e32 v86, v49
	v_mov_b32_e32 v87, v45
	v_mov_b32_e32 v88, v38
	v_mov_b32_e32 v89, v34
	v_pk_mul_f32 v[90:91], v[90:91], v[90:91]
	v_fmac_f32_e32 v97, v53, v53
	v_pk_fma_f32 v[70:71], v[74:75], v[74:75], v[70:71]
	v_add_f32_e32 v0, v0, v96
	v_mov_b32_e32 v92, v40
	v_mov_b32_e32 v93, v36
	v_pk_fma_f32 v[72:73], v[88:89], v[88:89], v[90:91]
	v_pk_fma_f32 v[70:71], v[86:87], v[86:87], v[70:71]
	v_add_f32_e32 v0, v0, v97
	v_mov_b32_e32 v94, v41
	v_mov_b32_e32 v95, v37
	v_pk_fma_f32 v[72:73], v[92:93], v[92:93], v[72:73]
	v_add_f32_e32 v0, v0, v70
	v_pk_fma_f32 v[72:73], v[94:95], v[94:95], v[72:73]
	v_add_f32_e32 v0, v0, v71
	v_add_f32_e32 v0, v0, v72
	v_add_f32_e32 v0, v0, v73
	v_lshl_add_u64 v[70:71], s[82:83], 0, v[64:65]
	v_cndmask_b32_e64 v73, 0, 1, s[22:23]
	v_add_co_u32_e32 v72, vcc, 0x6000000, v70
	v_cmp_ne_u32_e64 s[0:1], 1, v73
	v_addc_co_u32_e32 v73, vcc, 0, v71, vcc
	s_andn2_b64 vcc, exec, s[22:23]
	s_nop 1
	v_add_f32_dpp v0, v0, v0 quad_perm:[1,0,3,2] row_mask:0xf bank_mask:0xf
	s_nop 1
	v_add_f32_dpp v0, v0, v0 quad_perm:[2,3,0,1] row_mask:0xf bank_mask:0xf
	s_nop 1
	v_add_f32_dpp v0, v0, v0 row_half_mirror row_mask:0xf bank_mask:0xf
	s_nop 1
	v_add_f32_dpp v0, v0, v0 row_mirror row_mask:0xf bank_mask:0xf
	v_mov_b32_e32 v63, v0
	s_nop 1
	v_permlane16_swap_b32_e32 v63, v0
	v_add_f32_e32 v0, v0, v63
	v_mov_b32_e32 v63, v0
	s_nop 1
	v_permlane32_swap_b32_e32 v63, v0
	v_add_f32_e32 v0, v0, v63
	v_fmamk_f32 v0, v0, 0x3a000000, v178
	v_mul_f32_e32 v63, 0x4b800000, v0
	v_cmp_gt_f32_e64 s[8:9], s86, v0
	s_nop 1
	v_cndmask_b32_e64 v0, v0, v63, s[8:9]
	v_rsq_f32_e32 v0, v0
	s_nop 0
	v_mul_f32_e32 v63, 0x45800000, v0
	v_cndmask_b32_e64 v74, v0, v63, s[8:9]
	v_pk_mul_f32 v[76:77], v[76:77], v[74:75] op_sel_hi:[1,0]
	v_pk_mul_f32 v[86:87], v[78:79], v[74:75] op_sel_hi:[1,0]
	v_pk_mul_f32 v[78:79], v[2:3], v[76:77]
	v_pk_mul_f32 v[76:77], v[4:5], v[86:87]
	v_cvt_pk_bf16_f32 v86, v78, v79
	v_cvt_pk_bf16_f32 v87, v76, v77
	global_store_dwordx2 v[72:73], v[86:87], off
	v_lshl_add_u64 v[72:73], s[82:83], 0, v[66:67]
	s_cbranch_vccnz .LBB0_41
	v_mul_f32_e32 v0, 0x41800000, v78
	v_mul_f32_e32 v63, 0x41800000, v79
	v_mul_f32_e32 v75, 0x41800000, v76
	v_med3_f32 v0, v0, s93, v223
	v_med3_f32 v63, v63, s93, v223
	v_mov_b32_e32 v76, v1
	v_cvt_pk_fp8_f32 v76, v0, v63
	v_mul_f32_e32 v0, 0x41800000, v77
	v_med3_f32 v63, v75, s93, v223
	v_med3_f32 v0, v0, s93, v223
	v_cvt_pk_fp8_f32 v76, v63, v0 op_sel:[0,0,1]
	global_store_dword v[72:73], v76, off

; DI float bf2f(unsigned b) { return __uint_as_float(b << 16); }
; DI float wave_sum(float v) {
; #pragma unroll
;   for (int o = 32; o; o >>= 1) v += __shfl_xor(v, o);
;   return v;
; }
; DI void anorm_phase(u16* C, const float* __restrict__ gq, const float* __restrict__ gkv, unsigned char* __restrict__ cq8) {
;     ...
;   for (int row = gw; row < NTOK; row += nw) {
;     u32x4* cr = (u32x4*)(C + (size_t)row * 2048);
;     u32x4 v[4];
;     float sq = 0.f, skv = 0.f;
; #pragma unroll
;     for (int i = 0; i < 4; ++i) {
;       v[i] = cr[lane + 64 * i];
;       float s = 0.f;
; #pragma unroll
;       for (int j = 0; j < 4; ++j) { float a = bf2f(v[i][j] & 0xffffu), b = bf2f(v[i][j] >> 16); s += a * a + b * b; }
;       if (i < 3) sq += s; else skv += s;
;     }
;     sq = wave_sum(sq); skv = wave_sum(skv);
;     const float rq = rsqrtf(sq * (1.f / 1536.f) + 1e-6f), rkv = rsqrtf(skv * (1.f / 512.f) + 1e-6f);
.LBB0_980:
	v_lshl_add_u64 v[40:41], s[82:83], 0, v[38:39]
	global_load_dwordx4 v[42:45], v[40:41], off
	global_load_dwordx4 v[46:49], v[40:41], off offset:1024
	global_load_dwordx4 v[76:79], v[40:41], off offset:2048
	global_load_dwordx4 v[80:83], v[40:41], off offset:3072
	v_lshl_add_u64 v[64:65], s[82:83], 0, v[36:37]
	v_add_u32_e32 v34, s28, v34
	v_lshl_add_u64 v[36:37], v[36:37], 0, s[14:15]
	v_lshl_add_u64 v[38:39], v[38:39], 0, s[30:31]
	s_waitcnt vmcnt(3)
	v_and_b32_e32 v85, 0xffff0000, v45
	v_and_b32_e32 v87, 0xffff0000, v44
	v_and_b32_e32 v91, 0xffff0000, v42
	v_lshlrev_b32_e32 v84, 16, v45
	v_mul_f32_e32 v0, v85, v85
	v_lshlrev_b32_e32 v86, 16, v44
	v_and_b32_e32 v89, 0xffff0000, v43
	v_lshlrev_b32_e32 v90, 16, v42
	v_mov_b32_e32 v52, v87
	v_mov_b32_e32 v53, v91
	v_pk_fma_f32 v[50:51], v[84:85], v[84:85], v[0:1] op_sel_hi:[1,1,0]
	v_lshlrev_b32_e32 v88, 16, v43
	v_mul_f32_e32 v0, v89, v89
	v_mov_b32_e32 v42, v86
	v_mov_b32_e32 v43, v90
	v_pk_mul_f32 v[52:53], v[52:53], v[52:53]
	v_pk_fma_f32 v[44:45], v[88:89], v[88:89], v[0:1] op_sel_hi:[1,1,0]
	v_pk_fma_f32 v[42:43], v[42:43], v[42:43], v[52:53]
	s_waitcnt vmcnt(1)
	v_lshlrev_b32_e32 v52, 16, v79
	v_pk_add_f32 v[44:45], v[42:43], v[44:45] op_sel:[1,0] op_sel_hi:[0,1]
	v_and_b32_e32 v53, 0xffff0000, v79
	v_pk_add_f32 v[42:43], v[42:43], v[44:45]
	v_lshlrev_b32_e32 v60, 16, v49
	v_and_b32_e32 v61, 0xffff0000, v49
	v_lshlrev_b32_e32 v62, 16, v48
	v_and_b32_e32 v63, 0xffff0000, v48
	v_and_b32_e32 v67, 0xffff0000, v47
	v_pk_mul_f32 v[48:49], v[52:53], v[52:53]
	v_lshlrev_b32_e32 v66, 16, v47
	v_mul_f32_e32 v0, v67, v67
	v_and_b32_e32 v69, 0xffff0000, v46
	v_and_b32_e32 v55, 0xffff0000, v78
	v_mov_b32_e32 v51, v48
	v_mov_b32_e32 v43, v49
	v_pk_fma_f32 v[44:45], v[66:67], v[66:67], v[0:1] op_sel_hi:[1,1,0]
	v_lshlrev_b32_e32 v68, 16, v46
	v_mul_f32_e32 v0, v69, v69
	v_lshlrev_b32_e32 v54, 16, v78
	v_lshlrev_b32_e32 v56, 16, v77
	v_and_b32_e32 v57, 0xffff0000, v77
	v_pk_add_f32 v[42:43], v[50:51], v[42:43]
	v_mov_b32_e32 v50, v61
	v_mov_b32_e32 v51, v55
	v_pk_fma_f32 v[46:47], v[68:69], v[68:69], v[0:1] op_sel_hi:[1,1,0]
	v_pk_mul_f32 v[78:79], v[56:57], v[56:57]
	v_and_b32_e32 v59, 0xffff0000, v76
	v_mov_b32_e32 v48, v60
	v_mov_b32_e32 v49, v54
	v_pk_mul_f32 v[50:51], v[50:51], v[50:51]
	v_lshlrev_b32_e32 v58, 16, v76
	v_pk_fma_f32 v[48:49], v[48:49], v[48:49], v[50:51]
	v_mov_b32_e32 v47, v78
	v_mov_b32_e32 v45, v79
	v_mov_b32_e32 v50, v63
	v_mov_b32_e32 v51, v59
	v_pk_add_f32 v[44:45], v[46:47], v[44:45]
	v_mov_b32_e32 v46, v62
	v_mov_b32_e32 v47, v58
	v_pk_mul_f32 v[50:51], v[50:51], v[50:51]
	s_nop 0
	v_pk_fma_f32 v[46:47], v[46:47], v[46:47], v[50:51]
	s_nop 0
	v_pk_add_f32 v[44:45], v[46:47], v[44:45]
	s_nop 0
	v_pk_add_f32 v[44:45], v[48:49], v[44:45]
	s_nop 0
	v_pk_add_f32 v[50:51], v[42:43], v[44:45]
	s_waitcnt vmcnt(0)
	v_and_b32_e32 v43, 0xffff0000, v83
	v_and_b32_e32 v45, 0xffff0000, v82
	v_lshlrev_b32_e32 v42, 16, v83
	v_lshlrev_b32_e32 v44, 16, v82
	v_mov_b32_e32 v48, v43
	v_mov_b32_e32 v49, v45
	v_mov_b32_e32 v46, v42
	v_mov_b32_e32 v47, v44
	v_pk_mul_f32 v[48:49], v[48:49], v[48:49]
	s_nop 0
	v_pk_fma_f32 v[76:77], v[46:47], v[46:47], v[48:49]
	v_and_b32_e32 v47, 0xffff0000, v81
	v_and_b32_e32 v49, 0xffff0000, v80
	v_lshlrev_b32_e32 v46, 16, v81
	v_lshlrev_b32_e32 v48, 16, v80
	v_mov_b32_e32 v80, v49
	v_mov_b32_e32 v81, v47
	v_mov_b32_e32 v78, v48
	v_mov_b32_e32 v79, v46
	v_pk_mul_f32 v[80:81], v[80:81], v[80:81]
	s_nop 0
	v_pk_fma_f32 v[78:79], v[78:79], v[78:79], v[80:81]
	s_nop 0
	v_pk_add_f32 v[78:79], v[78:79], v[78:79] op_sel:[0,1] op_sel_hi:[1,0]
	s_nop 0
	v_pk_add_f32 v[78:79], v[76:77], v[78:79] op_sel:[1,0] op_sel_hi:[0,1]
	v_mov_b32_e32 v77, v50
	v_mov_b32_e32 v79, v51
	v_pk_add_f32 v[50:51], v[76:77], v[78:79]
	s_nop 1
	v_add_f32_dpp v50, v50, v50 quad_perm:[1,0,3,2] row_mask:0xf bank_mask:0xf
	v_add_f32_dpp v51, v51, v51 quad_perm:[1,0,3,2] row_mask:0xf bank_mask:0xf
	s_nop 1
	v_add_f32_dpp v50, v50, v50 quad_perm:[2,3,0,1] row_mask:0xf bank_mask:0xf
	v_add_f32_dpp v51, v51, v51 quad_perm:[2,3,0,1] row_mask:0xf bank_mask:0xf
	s_nop 1
	v_add_f32_dpp v50, v50, v50 row_half_mirror row_mask:0xf bank_mask:0xf
	v_add_f32_dpp v51, v51, v51 row_half_mirror row_mask:0xf bank_mask:0xf
	s_nop 1
	v_add_f32_dpp v50, v50, v50 row_mirror row_mask:0xf bank_mask:0xf
	v_add_f32_dpp v51, v51, v51 row_mirror row_mask:0xf bank_mask:0xf
	v_mov_b32_e32 v76, v50
	v_mov_b32_e32 v77, v51
	s_nop 1
	v_permlane16_swap_b32_e32 v76, v50
	v_permlane16_swap_b32_e32 v77, v51
	v_add_f32_e32 v50, v50, v76
	v_add_f32_e32 v51, v51, v77
	v_mov_b32_e32 v76, v50
	v_mov_b32_e32 v77, v51
	s_nop 1
	v_permlane32_swap_b32_e32 v76, v50
	v_permlane32_swap_b32_e32 v77, v51
	v_add_f32_e32 v50, v50, v76
	v_add_f32_e32 v51, v51, v77
	s_nop 0
	v_pk_fma_f32 v[50:51], v[50:51], s[22:23], v[178:179] op_sel_hi:[1,1,0]
	s_nop 0
	v_mul_f32_e32 v0, 0x4b800000, v51
	v_cmp_gt_f32_e64 s[0:1], s86, v51
	v_cmp_gt_f32_e32 vcc, s86, v50
	s_nop 0
	v_cndmask_b32_e64 v0, v51, v0, s[0:1]
	v_rsq_f32_e32 v0, v0
	s_nop 0
	v_mul_f32_e32 v35, 0x45800000, v0
	v_cndmask_b32_e64 v0, v0, v35, s[0:1]
; DI float bf2f(unsigned b) { return __uint_as_float(b << 16); }
; DI void anorm_phase(u16* C, const float* __restrict__ gq, const float* __restrict__ gkv, unsigned char* __restrict__ cq8) {
;     ...
; #pragma unroll
;     for (int i = 0; i < 4; ++i) {
;       const int col = (lane + 64 * i) * 8;
;       const float* gp = (i < 3) ? (gq + col) : (gkv + col - 1536);
;       const float r = (i < 3) ? rq : rkv;
;       const f32x4 g0 = *(const f32x4*)gp, g1 = *(const f32x4*)(gp + 4);
;       u32x4 o;
;       o[0] = pk2(bf2f(v[i][0] & 0xffffu) * r * g0[0], bf2f(v[i][0] >> 16) * r * g0[1]);
;       o[1] = pk2(bf2f(v[i][1] & 0xffffu) * r * g0[2], bf2f(v[i][1] >> 16) * r * g0[3]);
;       o[2] = pk2(bf2f(v[i][2] & 0xffffu) * r * g1[0], bf2f(v[i][2] >> 16) * r * g1[1]);
;       o[3] = pk2(bf2f(v[i][3] & 0xffffu) * r * g1[2], bf2f(v[i][3] >> 16) * r * g1[3]);
;       cr[lane + 64 * i] = o;
;       if (i < 3) {
;         const float q0 = bf2f(v[i][0] & 0xffffu) * r * g0[0] * CQ_SCALE, q1 = bf2f(v[i][0] >> 16) * r * g0[1] * CQ_SCALE;
;         const float q2 = bf2f(v[i][1] & 0xffffu) * r * g0[2] * CQ_SCALE, q3 = bf2f(v[i][1] >> 16) * r * g0[3] * CQ_SCALE;
;         const float q4 = bf2f(v[i][2] & 0xffffu) * r * g1[0] * CQ_SCALE, q5 = bf2f(v[i][2] >> 16) * r * g1[1] * CQ_SCALE;
;         const float q6 = bf2f(v[i][3] & 0xffffu) * r * g1[2] * CQ_SCALE, q7 = bf2f(v[i][3] >> 16) * r * g1[3] * CQ_SCALE;
;         u32x2 w8 = {pk4_fp8(q0, q1, q2, q3), pk4_fp8(q4, q5, q6, q7)};
;         *(u32x2*)(cq8 + (size_t)row * 1536 + col) = w8;
;       }
;     }
	v_pk_mul_f32 v[78:79], v[0:1], v[88:89] op_sel_hi:[0,1]
	v_pk_mul_f32 v[76:77], v[0:1], v[90:91] op_sel_hi:[0,1]
	v_pk_mul_f32 v[82:83], v[4:5], v[78:79]
	v_pk_mul_f32 v[78:79], v[0:1], v[86:87] op_sel_hi:[0,1]
	v_pk_mul_f32 v[84:85], v[0:1], v[84:85] op_sel_hi:[0,1]
	v_pk_mul_f32 v[80:81], v[2:3], v[76:77]
	v_pk_mul_f32 v[86:87], v[6:7], v[78:79]
	v_pk_mul_f32 v[84:85], v[8:9], v[84:85]
	v_cvt_pk_bf16_f32 v76, v80, v81
	v_cvt_pk_bf16_f32 v77, v82, v83
	v_cvt_pk_bf16_f32 v78, v86, v87
	v_cvt_pk_bf16_f32 v79, v84, v85
	global_store_dwordx4 v[40:41], v[76:79], off
	v_mul_f32_e32 v80, 0x41800000, v80
	v_mul_f32_e32 v81, 0x41800000, v81
	v_mul_f32_e32 v76, 0x41800000, v86
	v_mul_f32_e32 v77, 0x41800000, v87
	v_mul_f32_e32 v79, 0x41800000, v83
	v_med3_f32 v76, v76, s93, v223
	v_med3_f32 v77, v77, s93, v223
	v_mov_b32_e32 v83, v1
	v_mul_f32_e32 v78, 0x41800000, v82
	v_med3_f32 v80, v80, s93, v223
	v_med3_f32 v81, v81, s93, v223
	v_mov_b32_e32 v82, v1
	v_cvt_pk_fp8_f32 v83, v76, v77
	v_cvt_pk_fp8_f32 v82, v80, v81
	v_mul_f32_e32 v35, 0x41800000, v84
	v_mul_f32_e32 v51, 0x41800000, v85
	v_pk_mul_f32 v[68:69], v[0:1], v[68:69] op_sel_hi:[0,1]
	v_med3_f32 v35, v35, s93, v223
	v_med3_f32 v51, v51, s93, v223
	v_pk_mul_f32 v[68:69], v[10:11], v[68:69]
	v_pk_mul_f32 v[60:61], v[0:1], v[60:61] op_sel_hi:[0,1]
	v_med3_f32 v78, v78, s93, v223
	v_med3_f32 v79, v79, s93, v223
	v_cvt_pk_fp8_f32 v83, v35, v51 op_sel:[0,0,1]
	v_pk_mul_f32 v[60:61], v[16:17], v[60:61]
	v_mul_f32_e32 v35, 0x41800000, v68
	v_mul_f32_e32 v51, 0x41800000, v69
	v_cvt_pk_fp8_f32 v82, v78, v79 op_sel:[0,0,1]
	v_cvt_pk_bf16_f32 v76, v68, v69
	v_cvt_pk_bf16_f32 v79, v60, v61
	v_mul_f32_e32 v68, 0x41800000, v60
	v_med3_f32 v35, v35, s93, v223
	v_med3_f32 v51, v51, s93, v223
	v_mov_b32_e32 v60, v1
	v_pk_mul_f32 v[66:67], v[0:1], v[66:67] op_sel_hi:[0,1]
	v_cvt_pk_fp8_f32 v60, v35, v51
	v_pk_mul_f32 v[66:67], v[12:13], v[66:67]
	v_pk_mul_f32 v[62:63], v[0:1], v[62:63] op_sel_hi:[0,1]
	v_cvt_pk_bf16_f32 v77, v66, v67
	v_pk_mul_f32 v[62:63], v[14:15], v[62:63]
	v_mul_f32_e32 v66, 0x41800000, v66
	v_mul_f32_e32 v67, 0x41800000, v67
	v_cvt_pk_bf16_f32 v78, v62, v63
	v_mul_f32_e32 v62, 0x41800000, v62
	v_mul_f32_e32 v63, 0x41800000, v63
	v_med3_f32 v35, v66, s93, v223
	v_med3_f32 v51, v67, s93, v223
	v_mul_f32_e32 v69, 0x41800000, v61
	v_cvt_pk_fp8_f32 v60, v35, v51 op_sel:[0,0,1]
	v_med3_f32 v35, v62, s93, v223
	v_med3_f32 v51, v63, s93, v223
	v_mov_b32_e32 v61, v1
	v_cvt_pk_fp8_f32 v61, v35, v51
	v_med3_f32 v35, v68, s93, v223
	v_med3_f32 v51, v69, s93, v223
	s_brev_b32 s0, 32
	v_cvt_pk_fp8_f32 v61, v35, v51 op_sel:[0,0,1]
	v_pk_mul_f32 v[58:59], v[0:1], v[58:59] op_sel_hi:[0,1]
	v_add_co_u32_e64 v64, s[0:1], s0, v64
	v_pk_mul_f32 v[62:63], v[18:19], v[58:59]
	v_pk_mul_f32 v[56:57], v[0:1], v[56:57] op_sel_hi:[0,1]
	v_pk_mul_f32 v[52:53], v[0:1], v[52:53] op_sel_hi:[0,1]
	v_addc_co_u32_e64 v65, s[0:1], 0, v65, s[0:1]
	v_pk_mul_f32 v[56:57], v[20:21], v[56:57]
	v_pk_mul_f32 v[54:55], v[0:1], v[54:55] op_sel_hi:[0,1]
	v_pk_mul_f32 v[52:53], v[24:25], v[52:53]
	v_mul_f32_e32 v0, 0x41800000, v62
	v_mul_f32_e32 v35, 0x41800000, v63
	global_store_dwordx2 v[64:65], v[60:61], off offset:512
	v_cvt_pk_bf16_f32 v59, v56, v57
	v_cvt_pk_bf16_f32 v61, v52, v53
	v_mul_f32_e32 v51, 0x41800000, v56
	v_mul_f32_e32 v56, 0x41800000, v57
	v_mul_f32_e32 v57, 0x41800000, v52
	v_med3_f32 v0, v0, s93, v223
	v_med3_f32 v35, v35, s93, v223
	v_mov_b32_e32 v52, v1
	v_cvt_pk_fp8_f32 v52, v0, v35
	v_pk_mul_f32 v[54:55], v[22:23], v[54:55]
	v_cvt_pk_bf16_f32 v58, v62, v63
	v_cvt_pk_bf16_f32 v60, v54, v55
	v_mul_f32_e32 v54, 0x41800000, v54
	v_mul_f32_e32 v55, 0x41800000, v55
	v_med3_f32 v0, v51, s93, v223
	v_med3_f32 v35, v56, s93, v223
	global_store_dwordx4 v[40:41], v[58:61], off offset:2048
	v_cvt_pk_fp8_f32 v52, v0, v35 op_sel:[0,0,1]
	v_med3_f32 v0, v54, s93, v223
	v_mul_f32_e32 v58, 0x41800000, v53
	v_med3_f32 v35, v55, s93, v223
	v_mov_b32_e32 v53, v1
	v_cvt_pk_fp8_f32 v53, v0, v35
	v_med3_f32 v0, v57, s93, v223
	v_med3_f32 v35, v58, s93, v223
	global_store_dwordx2 v[64:65], v[82:83], off
	v_cvt_pk_fp8_f32 v53, v0, v35 op_sel:[0,0,1]
	v_mul_f32_e32 v0, 0x4b800000, v50
	v_cndmask_b32_e32 v0, v50, v0, vcc
	v_rsq_f32_e32 v0, v0
	global_store_dwordx4 v[40:41], v[76:79], off offset:1024
	global_store_dwordx2 v[64:65], v[52:53], off offset:1024
	v_mul_f32_e32 v35, 0x45800000, v0
	v_cndmask_b32_e32 v0, v0, v35, vcc
	v_pk_mul_f32 v[48:49], v[0:1], v[48:49] op_sel_hi:[0,1]
	v_pk_mul_f32 v[46:47], v[0:1], v[46:47] op_sel_hi:[0,1]
	v_pk_mul_f32 v[44:45], v[0:1], v[44:45] op_sel_hi:[0,1]
	v_pk_mul_f32 v[42:43], v[0:1], v[42:43] op_sel_hi:[0,1]
	v_pk_mul_f32 v[48:49], v[26:27], v[48:49]
	v_pk_mul_f32 v[46:47], v[28:29], v[46:47]
	v_pk_mul_f32 v[44:45], v[30:31], v[44:45]
	v_pk_mul_f32 v[42:43], v[32:33], v[42:43]
	v_cmp_lt_i32_e32 vcc, s87, v34
	v_cvt_pk_bf16_f32 v48, v48, v49
	v_cvt_pk_bf16_f32 v49, v46, v47
	v_cvt_pk_bf16_f32 v50, v44, v45
	v_cvt_pk_bf16_f32 v51, v42, v43
	s_or_b64 s[10:11], vcc, s[10:11]
	global_store_dwordx4 v[40:41], v[48:51], off offset:3072
	s_andn2_b64 exec, exec, s[10:11]
	s_cbranch_execnz .LBB0_980

; DI float wave_sum(float v) {
; #pragma unroll
;   for (int o = 32; o; o >>= 1) v += __shfl_xor(v, o);
;   return v;
; }
; template <bool F32OUT>
; DI void rmsnorm_rows(const float* X, const float* __restrict__ g, void* outp, int nrows, unsigned char* __restrict__ out8 = nullptr) {
;     ...
;   for (int row = gw; row < nrows; row += nw) {
;     const f32x4* xr = (const f32x4*)(X + (size_t)row * 2048);
;     f32x4 v[8];
;     float ss = 0.f;
; #pragma unroll
;     for (int i = 0; i < 8; ++i) { v[i] = xr[lane + 64 * i]; ss += v[i][0] * v[i][0] + v[i][1] * v[i][1] + v[i][2] * v[i][2] + v[i][3] * v[i][3]; }
;     ss = wave_sum(ss);
;     const float r = rsqrtf(ss * (1.f / 2048.f) + 1e-6f);
; #pragma unroll
;     for (int i = 0; i < 8; ++i) {
;       const f32x4 gg = ((const f32x4*)g)[lane + 64 * i];
;       f32x4 o = {v[i][0] * r * gg[0], v[i][1] * r * gg[1], v[i][2] * r * gg[2], v[i][3] * r * gg[3]};
;       if (F32OUT) ((f32x4*)((float*)outp + (size_t)row * 2048))[lane + 64 * i] = o;
.LBB0_1609:
	global_load_dwordx4 v[42:45], v[34:35], off offset:-4096
	global_load_dwordx4 v[46:49], v[34:35], off offset:-3072
	global_load_dwordx4 v[50:53], v[34:35], off offset:-2048
	global_load_dwordx4 v[54:57], v[34:35], off offset:-1024
	global_load_dwordx4 v[58:61], v[34:35], off
	global_load_dwordx4 v[62:65], v[34:35], off offset:1024
	global_load_dwordx4 v[66:69], v[34:35], off offset:2048
	global_load_dwordx4 v[70:73], v[34:35], off offset:3072
	v_add_u32_e32 v32, s28, v32
	v_cmp_lt_i32_e64 s[0:1], s5, v32
	s_or_b64 s[2:3], s[0:1], s[2:3]
	s_waitcnt vmcnt(7)
	v_mul_f32_e32 v90, v43, v43
	s_waitcnt vmcnt(6)
	v_mul_f32_e32 v91, v47, v47
	s_waitcnt vmcnt(5)
	v_mul_f32_e32 v92, v51, v51
	v_fmac_f32_e32 v90, v42, v42
	s_waitcnt vmcnt(3)
	v_mov_b32_e32 v76, v59
	s_waitcnt vmcnt(2)
	v_mov_b32_e32 v77, v63
	v_fmac_f32_e32 v91, v46, v46
	v_mul_f32_e32 v93, v55, v55
	v_mov_b32_e32 v74, v58
	v_mov_b32_e32 v75, v62
	v_pk_mul_f32 v[76:77], v[76:77], v[76:77]
	v_fmac_f32_e32 v92, v50, v50
	v_fmac_f32_e32 v90, v44, v44
	v_fmac_f32_e32 v91, v48, v48
	v_mov_b32_e32 v78, v60
	v_mov_b32_e32 v79, v64
	v_fmac_f32_e32 v93, v54, v54
	v_pk_fma_f32 v[74:75], v[74:75], v[74:75], v[76:77]
	v_fmac_f32_e32 v92, v52, v52
	v_fmac_f32_e32 v90, v45, v45
	v_fmac_f32_e32 v91, v49, v49
	s_waitcnt vmcnt(1)
	v_mov_b32_e32 v84, v67
	s_waitcnt vmcnt(0)
	v_mov_b32_e32 v85, v71
	v_fmac_f32_e32 v93, v56, v56
	v_fmac_f32_e32 v92, v53, v53
	v_pk_fma_f32 v[74:75], v[78:79], v[78:79], v[74:75]
	v_add_f32_e32 v78, v90, v91
	v_mov_b32_e32 v80, v61
	v_mov_b32_e32 v81, v65
	v_mov_b32_e32 v82, v66
	v_mov_b32_e32 v83, v70
	v_pk_mul_f32 v[84:85], v[84:85], v[84:85]
	v_fmac_f32_e32 v93, v57, v57
	v_add_f32_e32 v78, v78, v92
	v_mov_b32_e32 v86, v68
	v_mov_b32_e32 v87, v72
	v_pk_fma_f32 v[76:77], v[82:83], v[82:83], v[84:85]
	v_pk_fma_f32 v[74:75], v[80:81], v[80:81], v[74:75]
	v_add_f32_e32 v78, v78, v93
	v_mov_b32_e32 v88, v69
	v_mov_b32_e32 v89, v73
	v_pk_fma_f32 v[76:77], v[86:87], v[86:87], v[76:77]
	v_add_f32_e32 v74, v78, v74
	v_pk_fma_f32 v[76:77], v[88:89], v[88:89], v[76:77]
	v_add_f32_e32 v74, v74, v75
	v_add_f32_e32 v74, v74, v76
	v_add_f32_e32 v74, v74, v77
	s_nop 1
	v_add_f32_dpp v74, v74, v74 quad_perm:[1,0,3,2] row_mask:0xf bank_mask:0xf
	s_nop 1
	v_add_f32_dpp v74, v74, v74 quad_perm:[2,3,0,1] row_mask:0xf bank_mask:0xf
	s_nop 1
	v_add_f32_dpp v74, v74, v74 row_half_mirror row_mask:0xf bank_mask:0xf
	s_nop 1
	v_add_f32_dpp v74, v74, v74 row_mirror row_mask:0xf bank_mask:0xf
	v_mov_b32_e32 v75, v74
	s_nop 1
	v_permlane16_swap_b32_e32 v75, v74
	v_add_f32_e32 v74, v74, v75
	v_mov_b32_e32 v75, v74
	s_nop 1
	v_permlane32_swap_b32_e32 v75, v74
	v_add_f32_e32 v74, v74, v75
	v_fmamk_f32 v74, v74, 0x3a000000, v33
	v_mul_f32_e32 v75, 0x4b800000, v74
	v_cmp_gt_f32_e32 vcc, s4, v74
	s_nop 1
	v_cndmask_b32_e32 v74, v74, v75, vcc
	v_rsq_f32_e32 v74, v74
	s_nop 0
	v_mul_f32_e32 v75, 0x45800000, v74
	v_cndmask_b32_e32 v74, v74, v75, vcc
	v_pk_mul_f32 v[42:43], v[42:43], v[74:75] op_sel_hi:[1,0]
	v_pk_mul_f32 v[44:45], v[44:45], v[74:75] op_sel_hi:[1,0]
	v_pk_mul_f32 v[46:47], v[46:47], v[74:75] op_sel_hi:[1,0]
	v_pk_mul_f32 v[48:49], v[48:49], v[74:75] op_sel_hi:[1,0]
	v_pk_mul_f32 v[50:51], v[50:51], v[74:75] op_sel_hi:[1,0]
	v_pk_mul_f32 v[52:53], v[52:53], v[74:75] op_sel_hi:[1,0]
	v_pk_mul_f32 v[54:55], v[54:55], v[74:75] op_sel_hi:[1,0]
	v_pk_mul_f32 v[56:57], v[56:57], v[74:75] op_sel_hi:[1,0]
	v_pk_mul_f32 v[58:59], v[58:59], v[74:75] op_sel_hi:[1,0]
	v_pk_mul_f32 v[60:61], v[60:61], v[74:75] op_sel_hi:[1,0]
	v_pk_mul_f32 v[62:63], v[62:63], v[74:75] op_sel_hi:[1,0]
	v_pk_mul_f32 v[64:65], v[64:65], v[74:75] op_sel_hi:[1,0]
	v_pk_mul_f32 v[66:67], v[66:67], v[74:75] op_sel_hi:[1,0]
	v_pk_mul_f32 v[68:69], v[68:69], v[74:75] op_sel_hi:[1,0]
	v_pk_mul_f32 v[70:71], v[70:71], v[74:75] op_sel_hi:[1,0]
	v_pk_mul_f32 v[72:73], v[72:73], v[74:75] op_sel_hi:[1,0]
	v_pk_mul_f32 v[44:45], v[2:3], v[44:45]
	v_pk_mul_f32 v[42:43], v[0:1], v[42:43]
	v_pk_mul_f32 v[48:49], v[6:7], v[48:49]
	v_pk_mul_f32 v[46:47], v[4:5], v[46:47]
	v_pk_mul_f32 v[52:53], v[10:11], v[52:53]
	v_pk_mul_f32 v[50:51], v[8:9], v[50:51]
	v_pk_mul_f32 v[56:57], v[14:15], v[56:57]
	v_pk_mul_f32 v[54:55], v[12:13], v[54:55]
	v_pk_mul_f32 v[60:61], v[18:19], v[60:61]
	v_pk_mul_f32 v[58:59], v[16:17], v[58:59]
	v_pk_mul_f32 v[64:65], v[22:23], v[64:65]
	v_pk_mul_f32 v[62:63], v[20:21], v[62:63]
	v_pk_mul_f32 v[68:69], v[26:27], v[68:69]
	v_pk_mul_f32 v[66:67], v[24:25], v[66:67]
	v_pk_mul_f32 v[72:73], v[30:31], v[72:73]
	v_pk_mul_f32 v[70:71], v[28:29], v[70:71]
	global_store_dwordx4 v[34:35], v[42:45], off offset:-4096
	global_store_dwordx4 v[34:35], v[46:49], off offset:-3072
	global_store_dwordx4 v[34:35], v[50:53], off offset:-2048
	global_store_dwordx4 v[34:35], v[54:57], off offset:-1024
	global_store_dwordx4 v[34:35], v[58:61], off
	global_store_dwordx4 v[34:35], v[62:65], off offset:1024
	global_store_dwordx4 v[34:35], v[66:69], off offset:2048
	global_store_dwordx4 v[34:35], v[70:73], off offset:3072
	v_lshl_add_u64 v[34:35], v[34:35], 0, s[24:25]
	s_andn2_b64 exec, exec, s[2:3]
	s_cbranch_execnz .LBB0_1609
